# v12 + FoX tile loop: same max-chain/update-test edit as the MLA loop
# speedup vs baseline: 1.0102x; 1.0036x over previous
.LBB0_1272:
	v_max3_f32 v108, v115, v114, v116
	v_max3_f32 v109, v117, v14, v15
	v_max3_f32 v108, v108, v118, v119
	v_max3_f32 v109, v109, v6, v7
	v_max3_f32 v108, v108, v8, v9
	v_max3_f32 v109, v109, v4, v5
	v_max3_f32 v108, v108, v2, v3
	v_max3_f32 v109, v109, v98, v99
	v_max3_f32 v108, v108, v100, v101
	v_max3_f32 v109, v109, v110, v111
	v_max3_f32 v108, v108, v104, v105
	v_max3_f32 v109, v109, v106, v107
	v_max3_f32 v108, v108, v102, v103
	v_max3_f32 v109, v109, v12, v13
	v_max3_f32 v108, v108, v10, v11
	v_max_f32_e32 v108, v108, v109
	v_mov_b32_e32 v109, v108
	s_nop 1
	v_permlane32_swap_b32_e32 v108, v109
	v_max_f32_e32 v108, v108, v109
	v_cmp_lt_f32_e32 vcc, 0x41000000, v108
	s_or_b64 s[12:13], s[8:9], vcc
	v_cmp_lg_f32_e32 vcc, 0xff800000, v108
	s_and_b64 s[12:13], s[12:13], vcc
	s_cbranch_scc0 .LBB0_1276
	v_cndmask_b32_e64 v82, 0, v108, s[12:13]
	v_exp_f32_e64 v108, -v82
	s_xor_b64 s[12:13], s[12:13], -1
	v_add_f32_e32 v188, v188, v82
	s_or_b64 s[14:15], s[12:13], s[8:9]
	s_and_b64 s[12:13], s[8:9], s[12:13]
	v_xor_b32_e32 v80, 0x80000000, v188
	s_andn2_b64 s[8:9], s[8:9], exec
	s_and_b64 s[12:13], s[12:13], exec
	v_pk_add_f32 v[114:115], v[114:115], v[82:83] op_sel_hi:[1,0] neg_lo:[0,1] neg_hi:[0,1]
	v_pk_add_f32 v[98:99], v[98:99], v[82:83] op_sel_hi:[1,0] neg_lo:[0,1] neg_hi:[0,1]
	v_pk_add_f32 v[116:117], v[116:117], v[82:83] op_sel_hi:[1,0] neg_lo:[0,1] neg_hi:[0,1]
	v_pk_add_f32 v[100:101], v[100:101], v[82:83] op_sel_hi:[1,0] neg_lo:[0,1] neg_hi:[0,1]
	v_pk_add_f32 v[14:15], v[14:15], v[82:83] op_sel_hi:[1,0] neg_lo:[0,1] neg_hi:[0,1]
	v_pk_add_f32 v[110:111], v[110:111], v[82:83] op_sel_hi:[1,0] neg_lo:[0,1] neg_hi:[0,1]
	v_pk_add_f32 v[118:119], v[118:119], v[82:83] op_sel_hi:[1,0] neg_lo:[0,1] neg_hi:[0,1]
	v_pk_add_f32 v[104:105], v[104:105], v[82:83] op_sel_hi:[1,0] neg_lo:[0,1] neg_hi:[0,1]
	v_pk_add_f32 v[6:7], v[6:7], v[82:83] op_sel_hi:[1,0] neg_lo:[0,1] neg_hi:[0,1]
	v_pk_add_f32 v[106:107], v[106:107], v[82:83] op_sel_hi:[1,0] neg_lo:[0,1] neg_hi:[0,1]
	v_pk_add_f32 v[8:9], v[8:9], v[82:83] op_sel_hi:[1,0] neg_lo:[0,1] neg_hi:[0,1]
	v_pk_add_f32 v[102:103], v[102:103], v[82:83] op_sel_hi:[1,0] neg_lo:[0,1] neg_hi:[0,1]
	v_pk_add_f32 v[4:5], v[4:5], v[82:83] op_sel_hi:[1,0] neg_lo:[0,1] neg_hi:[0,1]
	v_pk_add_f32 v[12:13], v[12:13], v[82:83] op_sel_hi:[1,0] neg_lo:[0,1] neg_hi:[0,1]
	v_pk_add_f32 v[2:3], v[2:3], v[82:83] op_sel_hi:[1,0] neg_lo:[0,1] neg_hi:[0,1]
	v_pk_add_f32 v[10:11], v[10:11], v[82:83] op_sel_hi:[1,0] neg_lo:[0,1] neg_hi:[0,1]
	v_mov_b32_e32 v81, v80
	v_mov_b32_e32 v82, v80
	v_mov_b32_e32 v83, v80
	v_mov_b32_e32 v84, v80
	v_mov_b32_e32 v85, v80
	v_mov_b32_e32 v86, v80
	v_mov_b32_e32 v87, v80
	v_mov_b32_e32 v88, v80
	v_mov_b32_e32 v89, v80
	v_mov_b32_e32 v90, v80
	v_mov_b32_e32 v91, v80
	v_mov_b32_e32 v92, v80
	v_mov_b32_e32 v93, v80
	v_mov_b32_e32 v94, v80
	v_mov_b32_e32 v95, v80
	v_cndmask_b32_e64 v108, v108, 1.0, s[14:15]
	s_or_b64 s[8:9], s[8:9], s[12:13]
	s_branch .LBB0_1277
